# c12: c11 + P0 weight-transpose items re-dealt across the 8 waves (t=8q+wave: even deal, waves on adjacent items)
# baseline (speedup 1.0000x reference)
.LBB0_73:
	s_cmp_ge_u32 s37, s48
	s_cselect_b32 s1, 1, 0
	s_cmp_eq_u32 s48, 1
	s_cselect_b32 s1, s37, s1
	s_mul_i32 s2, s1, s48
	s_sub_i32 s2, s37, s2
	s_mul_i32 s0, s36, s1
	s_cmp_lt_i32 s0, 0x9580
	s_cselect_b64 s[4:5], -1, 0
	s_cmp_gt_i32 s0, 0x957f
	s_cbranch_scc1 .LBB0_84
	s_add_i32 s0, s0, s33
	s_add_i32 s0, s0, s2
	s_mov_b32 s56, -1
	s_cmp_gt_i32 s0, 0x957f
	s_mov_b32 s12, -1
	s_cbranch_scc1 .LBB0_76
	s_add_i32 s1, s0, 0x5600
	s_cmpk_gt_i32 s0, 0x55ff
	s_cselect_b32 s0, s1, s0
	s_add_i32 s1, s0, 0x4080
	s_cmp_gt_i32 s0, 0xc17f
	s_cselect_b32 s0, s1, s0
	s_add_i32 s1, s0, 0x1000
	s_cmp_gt_i32 s0, 0x129ff
	s_cselect_b32 s12, s1, s0

.LBB0_114:
	s_lshl_b32 s18, s67, 3
	s_add_i32 s18, s18, s37
	s_mul_hi_u32 s19, s18, s16
	s_not_b32 s4, s19
	s_mul_i32 s3, s48, s19
	s_mul_i32 s4, s48, s4
	s_sub_i32 s3, s18, s3
	s_add_i32 s4, s18, s4
	s_add_i32 s26, s19, 1
	s_cmp_ge_u32 s3, s48
	s_cselect_b32 s26, s26, s19
	s_cselect_b32 s3, s4, s3
	s_add_i32 s4, s26, 1
	s_cmp_ge_u32 s3, s48
	s_cselect_b32 s3, s4, s26
	s_mul_i32 s4, s3, s36
	s_cmp_lt_i32 s4, 0x9580
	s_cselect_b64 s[46:47], -1, 0
	s_cmp_gt_i32 s4, 0x957f
	s_cselect_b64 s[26:27], -1, 0
	s_and_b64 vcc, exec, s[26:27]
	s_cbranch_vccnz .LBB0_143
	s_mul_i32 s3, s3, s48
	s_sub_i32 s3, s4, s3
	s_add_i32 s3, s3, s18
	s_sub_i32 s3, s3, s67
	s_add_i32 s4, s33, s3
	s_add_i32 s22, s4, 0xffffaa00
	s_mov_b32 s17, -1
	s_cmp_gt_i32 s22, 0x957f
	s_mov_b32 s3, -1
	s_cbranch_scc1 .LBB0_117
	s_cmpk_gt_i32 s22, 0x55ff
	s_cselect_b32 s3, s4, s22
	s_add_i32 s4, s3, 0x4080
	s_cmp_gt_i32 s3, 0xc17f
	s_cselect_b32 s3, s4, s3
	s_add_i32 s4, s3, 0x1000
	s_cmp_gt_i32 s3, 0x129ff
	s_cselect_b32 s3, s4, s3
